# grid barrier: non-leader workgroups poll the cross-XCD generation word directly (one hop fewer)
# speedup vs baseline: 1.0063x; 1.0063x over previous
.LBB0_164:
	s_or_b64 exec, exec, s[10:11]
	v_cvt_f32_u32_e32 v4, v2
	s_waitcnt vmcnt(0)
	v_readfirstlane_b32 s8, v3
	v_sub_u32_e32 v3, 0, v2
	v_rcp_iflag_f32_e32 v4, v4
	v_add_u32_e32 v5, s8, v1
	v_mul_f32_e32 v4, 0x4f7ffffe, v4
	v_cvt_u32_f32_e32 v4, v4
	v_mul_lo_u32 v1, v3, v4
	v_mul_hi_u32 v1, v4, v1
	v_add_u32_e32 v1, v4, v1
	v_mul_hi_u32 v1, v5, v1
	v_mul_lo_u32 v3, v1, v2
	v_sub_u32_e32 v3, v5, v3
	v_add_u32_e32 v4, 1, v1
	v_cmp_ge_u32_e32 vcc, v3, v2
	s_nop 1
	v_cndmask_b32_e32 v1, v1, v4, vcc
	v_sub_u32_e32 v4, v3, v2
	v_cndmask_b32_e32 v3, v3, v4, vcc
	v_add_u32_e32 v4, 1, v1
	v_cmp_ge_u32_e32 vcc, v3, v2
	v_add_u32_e32 v3, 1, v5
	s_nop 0
	v_cndmask_b32_e32 v1, v1, v4, vcc
	v_mul_lo_u32 v4, v2, v1
	v_add_u32_e32 v2, v4, v2
	v_cmp_ne_u32_e32 vcc, v3, v2
	s_and_saveexec_b64 s[8:9], vcc
	s_xor_b64 s[8:9], exec, s[8:9]
	s_cbranch_execz .LBB0_178
	s_waitcnt lgkmcnt(0)
	v_mov_b32_e32 v0, 0x3100
	global_load_dword v0, v0, s[54:55] offset:1024 sc1
	s_add_u32 s12, s54, 0x3500
	s_addc_u32 s13, s55, 0
	s_waitcnt vmcnt(0)
	v_cmp_eq_u32_e32 vcc, v0, v1
	s_and_saveexec_b64 s[10:11], vcc
	s_cbranch_execz .LBB0_177
	s_mov_b32 s24, 1
	s_mov_b64 s[14:15], 0
	v_mov_b32_e32 v0, 0
	s_branch .LBB0_168

.LBB0_512:
	s_or_b64 exec, exec, s[14:15]
	v_cvt_f32_u32_e32 v4, v2
	s_waitcnt vmcnt(0)
	v_readfirstlane_b32 s4, v3
	v_sub_u32_e32 v3, 0, v2
	v_rcp_iflag_f32_e32 v4, v4
	v_add_u32_e32 v5, s4, v1
	v_mul_f32_e32 v4, 0x4f7ffffe, v4
	v_cvt_u32_f32_e32 v4, v4
	v_mul_lo_u32 v1, v3, v4
	v_mul_hi_u32 v1, v4, v1
	v_add_u32_e32 v1, v4, v1
	v_mul_hi_u32 v1, v5, v1
	v_mul_lo_u32 v3, v1, v2
	v_sub_u32_e32 v3, v5, v3
	v_add_u32_e32 v4, 1, v1
	v_cmp_ge_u32_e32 vcc, v3, v2
	s_nop 1
	v_cndmask_b32_e32 v1, v1, v4, vcc
	v_sub_u32_e32 v4, v3, v2
	v_cndmask_b32_e32 v3, v3, v4, vcc
	v_add_u32_e32 v4, 1, v1
	v_cmp_ge_u32_e32 vcc, v3, v2
	v_add_u32_e32 v3, 1, v5
	s_nop 0
	v_cndmask_b32_e32 v1, v1, v4, vcc
	v_mul_lo_u32 v4, v2, v1
	v_add_u32_e32 v2, v4, v2
	v_cmp_ne_u32_e32 vcc, v3, v2
	s_and_saveexec_b64 s[4:5], vcc
	s_xor_b64 s[12:13], exec, s[4:5]
	s_cbranch_execz .LBB0_526
	s_waitcnt lgkmcnt(0)
	v_mov_b32_e32 v0, 0x3100
	global_load_dword v0, v0, s[54:55] offset:1024 sc1
	s_add_u32 s16, s54, 0x3500
	s_addc_u32 s17, s55, 0
	s_waitcnt vmcnt(0)
	v_cmp_eq_u32_e32 vcc, v0, v1
	s_and_saveexec_b64 s[14:15], vcc
	s_cbranch_execz .LBB0_525
	s_mov_b32 s4, 1
	s_mov_b64 s[18:19], 0
	v_mov_b32_e32 v0, 0
	s_branch .LBB0_516

.LBB0_580:
	s_or_b64 exec, exec, s[12:13]
	v_cvt_f32_u32_e32 v4, v2
	s_waitcnt vmcnt(0)
	v_readfirstlane_b32 s4, v3
	v_sub_u32_e32 v3, 0, v2
	v_rcp_iflag_f32_e32 v4, v4
	v_add_u32_e32 v5, s4, v1
	v_mul_f32_e32 v4, 0x4f7ffffe, v4
	v_cvt_u32_f32_e32 v4, v4
	v_mul_lo_u32 v1, v3, v4
	v_mul_hi_u32 v1, v4, v1
	v_add_u32_e32 v1, v4, v1
	v_mul_hi_u32 v1, v5, v1
	v_mul_lo_u32 v3, v1, v2
	v_sub_u32_e32 v3, v5, v3
	v_add_u32_e32 v4, 1, v1
	v_cmp_ge_u32_e32 vcc, v3, v2
	s_nop 1
	v_cndmask_b32_e32 v1, v1, v4, vcc
	v_sub_u32_e32 v4, v3, v2
	v_cndmask_b32_e32 v3, v3, v4, vcc
	v_add_u32_e32 v4, 1, v1
	v_cmp_ge_u32_e32 vcc, v3, v2
	v_add_u32_e32 v3, 1, v5
	s_nop 0
	v_cndmask_b32_e32 v1, v1, v4, vcc
	v_mul_lo_u32 v4, v2, v1
	v_add_u32_e32 v2, v4, v2
	v_cmp_ne_u32_e32 vcc, v3, v2
	s_and_saveexec_b64 s[4:5], vcc
	s_xor_b64 s[10:11], exec, s[4:5]
	s_cbranch_execz .LBB0_594
	s_waitcnt lgkmcnt(0)
	v_mov_b32_e32 v0, 0x3100
	global_load_dword v0, v0, s[54:55] offset:1024 sc1
	s_add_u32 s14, s54, 0x3500
	s_addc_u32 s15, s55, 0
	s_waitcnt vmcnt(0)
	v_cmp_eq_u32_e32 vcc, v0, v1
	s_and_saveexec_b64 s[12:13], vcc
	s_cbranch_execz .LBB0_593
	s_mov_b32 s4, 1
	s_mov_b64 s[16:17], 0
	v_mov_b32_e32 v0, 0
	s_branch .LBB0_584

.LBB0_898:
	s_or_b64 exec, exec, s[6:7]
	s_waitcnt lgkmcnt(0)
	v_mov_b32_e32 v0, v242
	s_cmpk_gt_i32 s2, 0x2ff
	s_mov_b64 s[86:87], -1
	s_barrier
	s_cbranch_scc1 .LBB0_984
	s_load_dwordx2 s[62:63], s[0:1], 0xd0
	v_ashrrev_i32_e32 v218, 4, v0
	v_and_b32_e32 v0, 15, v0
	v_lshlrev_b32_e32 v7, 4, v0
	v_ashrrev_i32_e32 v12, 2, v243
	s_waitcnt lgkmcnt(0)
	s_add_u32 s4, s62, 0x8000000
	s_addc_u32 s5, s63, 0
	s_add_u32 s8, s62, 0xe000000
	s_addc_u32 s9, s63, 0
	s_add_i32 s12, 0, 0x11800
	v_and_b32_e32 v162, -8, v12
	v_add_u32_e32 v12, s12, v7
	s_add_i32 s12, 0, 0x15c00
	v_add_u32_e32 v13, s12, v7
	s_movk_i32 s12, 0x110
	v_and_b32_e32 v5, 15, v243
	s_and_b32 s15, s97, 32
	v_mul_lo_u32 v221, v218, s12
	s_add_i32 s12, 0, 0x1a400
	v_or_b32_e32 v219, s15, v5
	v_add_u32_e32 v14, s12, v7
	s_add_i32 s12, 0, 0x1e800
	v_and_b32_e32 v8, -16, v243
	v_add_u32_e32 v15, s12, v7
	v_add_u32_e32 v223, 0, v7
	v_mul_u32_u24_e32 v7, 0x110, v219
	s_add_i32 s13, s15, 32
	v_add3_u32 v224, 0, v7, v8
	v_and_or_b32 v7, s13, 32, v5
	v_mul_u32_u24_e32 v7, 0x110, v7
	s_add_i32 s14, s15, 48
	v_add3_u32 v225, 0, v7, v8
	v_and_or_b32 v7, s14, 48, v5
	v_mul_u32_u24_e32 v7, 0x110, v7
	s_add_i32 s16, s15, 0x60
	v_add3_u32 v226, 0, v7, v8
	v_and_or_b32 v7, s16, 32, v5
	s_bfe_u32 s11, s78, 0x10006
	s_lshr_b32 s12, s13, 6
	s_lshr_b32 s13, s14, 6
	s_lshr_b32 s14, s16, 6
	v_mul_u32_u24_e32 v7, 0x110, v7
	s_add_i32 s16, s15, 0x70
	v_add3_u32 v227, 0, v7, v8
	s_lshr_b32 s15, s16, 6
	v_and_or_b32 v7, s16, 48, v5
	s_add_i32 s16, s11, 3
	s_lshl_b32 s17, s16, 5
	s_lshr_b32 s10, s78, 7
	s_lshl_b32 s19, s11, 5
	s_lshr_b32 s16, s16, 1
	s_and_b32 s17, s17, 32
	s_add_u32 s66, s54, 0x200
	s_addc_u32 s67, s55, 0
	s_add_u32 s68, s54, 0x1000
	s_addc_u32 s69, s55, 0
	s_add_u32 s70, s54, 0x1100
	v_ashrrev_i32_e32 v1, 4, v243
	s_addc_u32 s71, s55, 0
	v_lshlrev_b32_e32 v160, 2, v1
	v_bfe_u32 v9, v243, 2, 2
	s_add_u32 s72, s54, 0x1200
	v_or_b32_e32 v10, v160, v9
	v_mul_u32_u24_e32 v7, 0x110, v7
	s_addc_u32 s73, s55, 0
	v_add3_u32 v228, 0, v7, v8
	v_add_u32_e32 v7, s19, v10
	v_xad_u32 v8, s19, 32, v10
	v_add_u32_e32 v10, s17, v10
	s_mul_i32 s17, s53, s52
	s_add_u32 s74, s54, 0x1300
	s_mul_i32 s17, s17, s75
	s_addc_u32 s75, s55, 0
	v_writelane_b32 v255, s76, 4
	s_cmp_eq_u32 s3, 15
	s_cselect_b64 s[20:21], -1, 0
	v_writelane_b32 v255, s77, 5
	v_writelane_b32 v255, s20, 2
	s_cmp_eq_u32 s3, 14
	v_and_b32_e32 v6, 3, v243
	v_writelane_b32 v255, s21, 3
	s_cselect_b64 s[20:21], -1, 0
	v_writelane_b32 v255, s20, 6
	s_cmp_eq_u32 s3, 13
	s_movk_i32 s18, 0x120
	v_writelane_b32 v255, s21, 7
	s_cselect_b64 s[20:21], -1, 0
	v_writelane_b32 v255, s20, 8
	s_cmp_eq_u32 s3, 12
	v_lshlrev_b32_e32 v11, 3, v6
	v_writelane_b32 v255, s21, 9
	s_cselect_b64 s[20:21], -1, 0
	v_writelane_b32 v255, s20, 10
	s_cmp_eq_u32 s3, 11
	v_mul_lo_u32 v7, v7, s18
	v_writelane_b32 v255, s21, 11
	s_cselect_b64 s[20:21], -1, 0
	v_writelane_b32 v255, s20, 12
	s_cmp_eq_u32 s3, 10
	v_add_u32_e32 v232, s19, v160
	v_writelane_b32 v255, s21, 13
	s_cselect_b64 s[20:21], -1, 0
	v_writelane_b32 v255, s20, 14
	s_cmp_eq_u32 s3, 9
	v_lshlrev_b32_e32 v4, 3, v0
	v_writelane_b32 v255, s21, 15
	s_cselect_b64 s[20:21], -1, 0
	v_writelane_b32 v255, s20, 16
	s_cmp_eq_u32 s3, 8
	v_mov_b32_e32 v0, 0x3f80
	v_writelane_b32 v255, s21, 17
	s_cselect_b64 s[20:21], -1, 0
	v_writelane_b32 v255, s20, 18
	s_cmp_eq_u32 s3, 7
	v_cmp_eq_u32_e32 vcc, 0, v6
	v_writelane_b32 v255, s21, 19
	s_cselect_b64 s[20:21], -1, 0
	v_writelane_b32 v255, s20, 20
	s_cmp_eq_u32 s3, 6
	v_add3_u32 v229, 0, v7, v11
	v_writelane_b32 v255, s21, 21
	s_cselect_b64 s[20:21], -1, 0
	v_writelane_b32 v255, s20, 22
	s_cmp_eq_u32 s3, 5
	v_or_b32_e32 v7, v232, v9
	v_writelane_b32 v255, s21, 23
	s_cselect_b64 s[20:21], -1, 0
	s_cmp_eq_u32 s3, 4
	s_cselect_b64 s[30:31], -1, 0
	s_cmp_eq_u32 s3, 3
	s_cselect_b64 s[34:35], -1, 0
	s_cmp_eq_u32 s3, 2
	s_cselect_b64 s[36:37], -1, 0
	s_cmp_eq_u32 s3, 1
	v_writelane_b32 v255, s20, 24
	s_cselect_b64 s[38:39], -1, 0
	s_cmp_eq_u32 s3, 0
	v_writelane_b32 v255, s21, 25
	s_cselect_b64 s[40:41], -1, 0
	s_lshl_b32 s20, s3, 8
	s_add_u32 s20, s54, s20
	s_addc_u32 s21, s55, 0
	s_add_u32 s76, s20, 0x1400
	s_addc_u32 s77, s21, 0
	s_add_u32 s78, s20, 0x2400
	s_addc_u32 s79, s21, 0
	s_add_u32 s100, s54, 0x3500
	s_addc_u32 s101, s55, 0
	s_add_u32 s80, s54, 0x3400
	v_cndmask_b32_e32 v0, 0, v0, vcc
	s_mov_b32 s6, 0x5040100
	s_addc_u32 s81, s55, 0
	v_mul_lo_u32 v7, v7, s18
	v_lshlrev_b32_e32 v158, 3, v1
	v_perm_b32 v0, v0, v0, s6
	v_and_b32_e32 v6, 16, v243
	v_mul_lo_u32 v222, v218, s18
	v_mul_lo_u32 v8, v8, s18
	v_mul_lo_u32 v10, v10, s18
	s_add_u32 s82, s54, 0x3500
	v_or_b32_e32 v7, v7, v11
	v_or_b32_e32 v234, s19, v5
	s_mov_b32 s65, 0
	v_mov_b32_e32 v157, 0
	v_ashrrev_i32_e32 v159, 31, v158
	v_sub_u32_e32 v220, v5, v160
	v_mov_b32_e32 v1, v0
	v_mov_b32_e32 v2, v0
	v_mov_b32_e32 v3, v0
	v_ashrrev_i32_e32 v161, 31, v160
	v_ashrrev_i32_e32 v163, 31, v162
	v_cmp_gt_u32_e64 s[6:7], 16, v243
	s_addc_u32 s83, s55, 0
	v_add3_u32 v230, 0, v8, v11
	v_add3_u32 v231, 0, v10, v11
	v_add_u32_e32 v233, 0, v7
	v_or_b32_e32 v235, 0x50, v234
	v_add_u32_e32 v254, 0x60, v218
	v_or_b32_e32 v238, 16, v234
	s_mov_b64 s[84:85], 0
	s_add_i32 s18, 0, 0x243c0
	s_add_i32 s19, 0, 0x243c4
	v_mov_b32_e32 v239, 0xc2000
	s_movk_i32 s20, 0x1800
	v_lshlrev_b32_e32 v164, 1, v4
	s_movk_i32 s21, 0xc00
	v_add_u32_e32 v240, v12, v221
	v_add_u32_e32 v241, v13, v222
	v_add_u32_e32 v243, v14, v221
	v_add_u32_e32 v244, v15, v222
	v_lshlrev_b32_e32 v166, 1, v6
	s_mov_b32 s22, 0x3f317218
	v_mov_b32_e32 v245, 0xff61b1e6
	s_branch .LBB0_901

.LBB0_920:
	s_or_b64 exec, exec, s[48:49]
	v_cvt_f32_u32_e32 v56, v54
	s_waitcnt vmcnt(0)
	v_readfirstlane_b32 s23, v55
	v_sub_u32_e32 v55, 0, v54
	v_rcp_iflag_f32_e32 v56, v56
	v_add_u32_e32 v57, s23, v53
	v_mul_f32_e32 v56, 0x4f7ffffe, v56
	v_cvt_u32_f32_e32 v56, v56
	v_mul_lo_u32 v53, v55, v56
	v_mul_hi_u32 v53, v56, v53
	v_add_u32_e32 v53, v56, v53
	v_mul_hi_u32 v53, v57, v53
	v_mul_lo_u32 v55, v53, v54
	v_sub_u32_e32 v55, v57, v55
	v_add_u32_e32 v56, 1, v53
	v_cmp_ge_u32_e32 vcc, v55, v54
	s_nop 1
	v_cndmask_b32_e32 v53, v53, v56, vcc
	v_sub_u32_e32 v56, v55, v54
	v_cndmask_b32_e32 v55, v55, v56, vcc
	v_add_u32_e32 v56, 1, v53
	v_cmp_ge_u32_e32 vcc, v55, v54
	v_add_u32_e32 v55, 1, v57
	s_nop 0
	v_cndmask_b32_e32 v53, v53, v56, vcc
	v_mul_lo_u32 v56, v54, v53
	v_add_u32_e32 v54, v56, v54
	v_cmp_ne_u32_e32 vcc, v55, v54
	s_and_saveexec_b64 s[24:25], vcc
	s_xor_b64 s[48:49], exec, s[24:25]
	s_cbranch_execz .LBB0_934
	s_waitcnt lgkmcnt(0)
	global_load_dword v52, v157, s[100:101] sc1
	s_waitcnt vmcnt(0)
	v_cmp_eq_u32_e32 vcc, v52, v53
	s_and_saveexec_b64 s[50:51], vcc
	s_cbranch_execz .LBB0_933
	s_mov_b32 s23, 1
	s_mov_b64 s[84:85], 0
	s_branch .LBB0_924

.LBB0_928:
	global_load_dword v52, v157, s[100:101] sc1
	s_add_i32 s23, s23, 1
	s_mov_b64 s[90:91], -1
	s_waitcnt vmcnt(0)
	v_cmp_ne_u32_e32 vcc, v52, v53
	s_orn2_b64 s[88:89], vcc, exec
	s_branch .LBB0_923

.LBB0_1003:
	s_or_b64 exec, exec, s[12:13]
	v_cvt_f32_u32_e32 v4, v2
	s_waitcnt vmcnt(0)
	v_readfirstlane_b32 s2, v3
	v_sub_u32_e32 v3, 0, v2
	v_rcp_iflag_f32_e32 v4, v4
	v_add_u32_e32 v5, s2, v1
	v_mul_f32_e32 v4, 0x4f7ffffe, v4
	v_cvt_u32_f32_e32 v4, v4
	v_mul_lo_u32 v1, v3, v4
	v_mul_hi_u32 v1, v4, v1
	v_add_u32_e32 v1, v4, v1
	v_mul_hi_u32 v1, v5, v1
	v_mul_lo_u32 v3, v1, v2
	v_sub_u32_e32 v3, v5, v3
	v_add_u32_e32 v4, 1, v1
	v_cmp_ge_u32_e32 vcc, v3, v2
	s_nop 1
	v_cndmask_b32_e32 v1, v1, v4, vcc
	v_sub_u32_e32 v4, v3, v2
	v_cndmask_b32_e32 v3, v3, v4, vcc
	v_add_u32_e32 v4, 1, v1
	v_cmp_ge_u32_e32 vcc, v3, v2
	v_add_u32_e32 v3, 1, v5
	s_nop 0
	v_cndmask_b32_e32 v1, v1, v4, vcc
	v_mul_lo_u32 v4, v2, v1
	v_add_u32_e32 v2, v4, v2
	v_cmp_ne_u32_e32 vcc, v3, v2
	s_and_saveexec_b64 s[4:5], vcc
	s_xor_b64 s[10:11], exec, s[4:5]
	s_cbranch_execz .LBB0_1017
	s_waitcnt lgkmcnt(0)
	v_mov_b32_e32 v0, 0x3100
	global_load_dword v0, v0, s[54:55] offset:1024 sc1
	s_add_u32 s14, s54, 0x3500
	s_addc_u32 s15, s55, 0
	s_waitcnt vmcnt(0)
	v_cmp_eq_u32_e32 vcc, v0, v1
	s_and_saveexec_b64 s[12:13], vcc
	s_cbranch_execz .LBB0_1016
	s_mov_b32 s2, 1
	s_mov_b64 s[16:17], 0
	v_mov_b32_e32 v0, 0
	s_branch .LBB0_1007

.LBB0_1150:
	s_or_b64 exec, exec, s[14:15]
	v_cvt_f32_u32_e32 v4, v2
	s_waitcnt vmcnt(0)
	v_readfirstlane_b32 s2, v3
	v_sub_u32_e32 v3, 0, v2
	v_rcp_iflag_f32_e32 v4, v4
	v_add_u32_e32 v5, s2, v1
	v_mul_f32_e32 v4, 0x4f7ffffe, v4
	v_cvt_u32_f32_e32 v4, v4
	v_mul_lo_u32 v1, v3, v4
	v_mul_hi_u32 v1, v4, v1
	v_add_u32_e32 v1, v4, v1
	v_mul_hi_u32 v1, v5, v1
	v_mul_lo_u32 v3, v1, v2
	v_sub_u32_e32 v3, v5, v3
	v_add_u32_e32 v4, 1, v1
	v_cmp_ge_u32_e32 vcc, v3, v2
	s_nop 1
	v_cndmask_b32_e32 v1, v1, v4, vcc
	v_sub_u32_e32 v4, v3, v2
	v_cndmask_b32_e32 v3, v3, v4, vcc
	v_add_u32_e32 v4, 1, v1
	v_cmp_ge_u32_e32 vcc, v3, v2
	v_add_u32_e32 v3, 1, v5
	s_nop 0
	v_cndmask_b32_e32 v1, v1, v4, vcc
	v_mul_lo_u32 v4, v2, v1
	v_add_u32_e32 v2, v4, v2
	v_cmp_ne_u32_e32 vcc, v3, v2
	s_and_saveexec_b64 s[4:5], vcc
	s_xor_b64 s[12:13], exec, s[4:5]
	s_cbranch_execz .LBB0_1164
	s_waitcnt lgkmcnt(0)
	v_mov_b32_e32 v0, 0x3100
	global_load_dword v0, v0, s[54:55] offset:1024 sc1
	s_add_u32 s16, s54, 0x3500
	s_addc_u32 s17, s55, 0
	s_waitcnt vmcnt(0)
	v_cmp_eq_u32_e32 vcc, v0, v1
	s_and_saveexec_b64 s[14:15], vcc
	s_cbranch_execz .LBB0_1163
	s_mov_b32 s2, 1
	s_mov_b64 s[18:19], 0
	v_mov_b32_e32 v0, 0
	s_branch .LBB0_1154

.LBB0_1218:
	s_or_b64 exec, exec, s[12:13]
	v_cvt_f32_u32_e32 v4, v2
	s_waitcnt vmcnt(0)
	v_readfirstlane_b32 s2, v3
	v_sub_u32_e32 v3, 0, v2
	v_rcp_iflag_f32_e32 v4, v4
	v_add_u32_e32 v5, s2, v1
	v_mul_f32_e32 v4, 0x4f7ffffe, v4
	v_cvt_u32_f32_e32 v4, v4
	v_mul_lo_u32 v1, v3, v4
	v_mul_hi_u32 v1, v4, v1
	v_add_u32_e32 v1, v4, v1
	v_mul_hi_u32 v1, v5, v1
	v_mul_lo_u32 v3, v1, v2
	v_sub_u32_e32 v3, v5, v3
	v_add_u32_e32 v4, 1, v1
	v_cmp_ge_u32_e32 vcc, v3, v2
	s_nop 1
	v_cndmask_b32_e32 v1, v1, v4, vcc
	v_sub_u32_e32 v4, v3, v2
	v_cndmask_b32_e32 v3, v3, v4, vcc
	v_add_u32_e32 v4, 1, v1
	v_cmp_ge_u32_e32 vcc, v3, v2
	v_add_u32_e32 v3, 1, v5
	s_nop 0
	v_cndmask_b32_e32 v1, v1, v4, vcc
	v_mul_lo_u32 v4, v2, v1
	v_add_u32_e32 v2, v4, v2
	v_cmp_ne_u32_e32 vcc, v3, v2
	s_and_saveexec_b64 s[2:3], vcc
	s_xor_b64 s[10:11], exec, s[2:3]
	s_cbranch_execz .LBB0_1232
	s_waitcnt lgkmcnt(0)
	v_mov_b32_e32 v0, 0x3100
	global_load_dword v0, v0, s[54:55] offset:1024 sc1
	s_add_u32 s14, s54, 0x3500
	s_addc_u32 s15, s55, 0
	s_waitcnt vmcnt(0)
	v_cmp_eq_u32_e32 vcc, v0, v1
	s_and_saveexec_b64 s[12:13], vcc
	s_cbranch_execz .LBB0_1231
	s_mov_b32 s2, 1
	s_mov_b64 s[16:17], 0
	v_mov_b32_e32 v0, 0
	s_branch .LBB0_1222
